# i/f-gate GEMM loop: second dead B chunk (rows 64..127, never read by EpiIF) no longer loaded; counted waits 6 -> 5
# speedup vs baseline: 1.0080x; 1.0040x over previous
; #define PG8_STAGE(bufoff, gbase, voff) do { _Pragma("unroll") for (int _i = 0; _i < 2; ++_i) \
;         __builtin_amdgcn_global_load_lds((const unsigned*)((const char*)(gbase) + (voff)[_i]), (PG8_LAS unsigned*)(lds + (bufoff) + ldsw + _i * 8192), 16, 0, 0); } while (0)
; #define PG8_LDA(dst, b, h) do { _Pragma("unroll") for (int m = 0; m < 4; ++m) _Pragma("unroll") for (int k = 0; k < 2; ++k) dst[m][k] = *(const PG8_LAS bf16x8*)(lds + PG8_SA(b, h) + aoff + m * 2048 + k * 1024); } while (0)
; #define PG8_LDB(dst, b, h) do { _Pragma("unroll") for (int n = 0; n < 2; ++n) _Pragma("unroll") for (int k = 0; k < 2; ++k) dst[n][k] = *(const PG8_LAS bf16x8*)(lds + PG8_SB(b, h) + boff + n * 2048 + k * 1024); } while (0)
; #define PG8_MMA(ai, bj, At, Bt) do { __builtin_amdgcn_s_setprio(1); _Pragma("unroll") for (int m = 0; m < 4; ++m) _Pragma("unroll") for (int n = 0; n < 2; ++n) _Pragma("unroll") for (int k = 0; k < 2; ++k) \
;         acc[ai][bj][m][n] = __builtin_amdgcn_mfma_f32_16x16x32_bf16(Bt[n][k], At[m][k], acc[ai][bj][m][n], 0, 0, 0); __builtin_amdgcn_s_setprio(0); } while (0)
; #define PG8_WAIT_V(n) asm volatile("s_waitcnt vmcnt(" #n ")" ::: "memory")
; #define PG8_WAIT_L(n) asm volatile("s_waitcnt lgkmcnt(" #n ")" ::: "memory")
; #define PG8_BAR __builtin_amdgcn_s_barrier()
; #define PG8_SCHED __builtin_amdgcn_sched_barrier(0)
; template <class Epi, class Sched, bool ALIGN_EPI = false, bool SP2 = false>
; __device__ __forceinline__ void gemm_phase(PG8_LAS unsigned char* lds, const Gemm g, const Sched& S, const Epi& E) {
;     ...
;             PG8_LDB(B0, 0, 0); PG8_LDB(B1, 0, 1); PG8_SCHED; PG8_LDA(At, 0, 0); PG8_STAGE(PG8_SA(1, 1), a1 + hstep, voffA);
;             PG8_WAIT_V(8); PG8_WAIT_L(0); PG8_BAR; PG8_MMA(0, 0, At, B0); PG8_MMA(0, 1, At, B1); PG8_BAR; PG8_SCHED;
;             PG8_LDA(At, 0, 1); PG8_STAGE(PG8_SB(0, 0), b2, voffB); PG8_STAGE(PG8_SB(0, 1), b2 + hstep, voffB); PG8_STAGE(PG8_SA(0, 0), a2, voffA);
;             PG8_WAIT_V(8); PG8_WAIT_L(0); PG8_BAR; PG8_MMA(1, 0, At, B0); PG8_MMA(1, 1, At, B1); PG8_BAR; PG8_SCHED;
.LBB0_229:
	s_add_u32 s22, s20, 0xfffc0080
	s_addc_u32 s23, s21, -1
	s_add_i32 s47, 0, 0x10000
	v_add_u32_e32 v88, s47, v91
	ds_read_b128 v[18:21], v88
	ds_read_b128 v[22:25], v88 offset:1024
	ds_read_b128 v[94:97], v88 offset:2048
	ds_read_b128 v[98:101], v88 offset:3072
	s_cmp_eq_u32 s46, 12
	s_cselect_b32 s25, s15, s23
	s_cselect_b32 s24, s42, s22
	s_cselect_b32 s23, s9, s45
	s_cselect_b32 s22, s43, s44
	v_lshl_add_u64 v[88:89], s[20:21], 0, v[84:85]
	s_add_i32 m0, s29, 0xc000
	ds_read_b128 v[102:105], v92
	ds_read_b128 v[106:109], v92 offset:1024
	ds_read_b128 v[110:113], v92 offset:2048
	ds_read_b128 v[114:117], v92 offset:3072
	ds_read_b128 v[118:121], v92 offset:4096
	ds_read_b128 v[122:125], v92 offset:5120
	ds_read_b128 v[126:129], v92 offset:6144
	ds_read_b128 v[130:133], v92 offset:7168
	global_load_lds_dwordx4 v[88:89], off
	v_lshl_add_u64 v[88:89], s[20:21], 0, v[86:87]
	s_add_i32 m0, s29, 0xe000
	s_nop 0
	global_load_lds_dwordx4 v[88:89], off
	s_waitcnt vmcnt(5)
	s_waitcnt lgkmcnt(0)
	s_barrier
	s_setprio 1
	s_waitcnt lgkmcnt(0)
	v_mfma_f32_16x16x32_bf16 v[70:73], v[18:21], v[102:105], v[70:73]
	v_mfma_f32_16x16x32_bf16 v[66:69], v[94:97], v[102:105], v[66:69]
	v_mfma_f32_16x16x32_bf16 v[62:65], v[18:21], v[110:113], v[62:65]
	v_mfma_f32_16x16x32_bf16 v[58:61], v[94:97], v[110:113], v[58:61]
	v_mfma_f32_16x16x32_bf16 v[54:57], v[18:21], v[118:121], v[54:57]
	v_mfma_f32_16x16x32_bf16 v[50:53], v[94:97], v[118:121], v[50:53]
	v_mfma_f32_16x16x32_bf16 v[46:49], v[18:21], v[126:129], v[46:49]
	v_mfma_f32_16x16x32_bf16 v[42:45], v[94:97], v[126:129], v[42:45]
	v_mfma_f32_16x16x32_bf16 v[70:73], v[22:25], v[106:109], v[70:73]
	v_mfma_f32_16x16x32_bf16 v[66:69], v[98:101], v[106:109], v[66:69]
	v_mfma_f32_16x16x32_bf16 v[62:65], v[22:25], v[114:117], v[62:65]
	v_mfma_f32_16x16x32_bf16 v[58:61], v[98:101], v[114:117], v[58:61]
	v_mfma_f32_16x16x32_bf16 v[54:57], v[22:25], v[122:125], v[54:57]
	v_mfma_f32_16x16x32_bf16 v[50:53], v[98:101], v[122:125], v[50:53]
	v_mfma_f32_16x16x32_bf16 v[46:49], v[22:25], v[130:133], v[46:49]
	v_mfma_f32_16x16x32_bf16 v[42:45], v[98:101], v[130:133], v[42:45]
	s_setprio 0
	s_setprio 1
	s_setprio 0
	s_barrier
	s_add_i32 s47, s47, s28
	v_lshl_add_u64 v[88:89], s[22:23], 0, v[78:79]
	s_mov_b32 m0, s47
	ds_read_b128 v[102:105], v92 offset:16384
	ds_read_b128 v[106:109], v92 offset:17408
	ds_read_b128 v[110:113], v92 offset:18432
	ds_read_b128 v[114:117], v92 offset:19456
	ds_read_b128 v[118:121], v92 offset:20480
	ds_read_b128 v[122:125], v92 offset:21504
	ds_read_b128 v[126:129], v92 offset:22528
	ds_read_b128 v[130:133], v92 offset:23552
	global_load_lds_dwordx4 v[88:89], off
	s_add_i32 m0, s47, 0x2000
	s_add_u32 s48, s22, 0x40000
	v_lshl_add_u64 v[134:135], s[22:23], 0, v[74:75]
	s_addc_u32 s49, s23, 0
	v_lshl_add_u64 v[136:137], s[48:49], 0, v[78:79]
	s_mov_b32 m0, s30
	v_lshl_add_u64 v[138:139], s[24:25], 0, v[76:77]
	v_lshl_add_u64 v[136:137], s[48:49], 0, v[74:75]
	s_mov_b32 m0, s31
	s_nop 0
	v_lshl_add_u64 v[136:137], s[24:25], 0, v[0:1]
	s_mov_b32 m0, s29
	s_nop 0
	global_load_lds_dwordx4 v[136:137], off
	s_mov_b32 m0, s33
	s_nop 0
	global_load_lds_dwordx4 v[138:139], off
	s_waitcnt vmcnt(5)
	s_waitcnt lgkmcnt(0)
	s_barrier
	s_setprio 1
	s_waitcnt lgkmcnt(0)
	v_mfma_f32_16x16x32_bf16 v[38:41], v[18:21], v[102:105], v[38:41]
	v_mfma_f32_16x16x32_bf16 v[34:37], v[94:97], v[102:105], v[34:37]
	v_mfma_f32_16x16x32_bf16 v[30:33], v[18:21], v[110:113], v[30:33]
	v_mfma_f32_16x16x32_bf16 v[26:29], v[94:97], v[110:113], v[26:29]
	v_mfma_f32_16x16x32_bf16 v[14:17], v[18:21], v[118:121], v[14:17]
	v_mfma_f32_16x16x32_bf16 v[10:13], v[94:97], v[118:121], v[10:13]
	v_mfma_f32_16x16x32_bf16 v[6:9], v[18:21], v[126:129], v[6:9]
	v_mfma_f32_16x16x32_bf16 v[2:5], v[94:97], v[126:129], v[2:5]
	v_mfma_f32_16x16x32_bf16 v[38:41], v[22:25], v[106:109], v[38:41]
	v_mfma_f32_16x16x32_bf16 v[34:37], v[98:101], v[106:109], v[34:37]
	v_mfma_f32_16x16x32_bf16 v[30:33], v[22:25], v[114:117], v[30:33]
	v_mfma_f32_16x16x32_bf16 v[26:29], v[98:101], v[114:117], v[26:29]
	v_mfma_f32_16x16x32_bf16 v[14:17], v[22:25], v[122:125], v[14:17]
	v_mfma_f32_16x16x32_bf16 v[10:13], v[98:101], v[122:125], v[10:13]
	v_mfma_f32_16x16x32_bf16 v[6:9], v[22:25], v[130:133], v[6:9]
	v_mfma_f32_16x16x32_bf16 v[2:5], v[98:101], v[130:133], v[2:5]
	s_setprio 0
	s_setprio 1
	s_setprio 0
	s_barrier
; #define PG8_STAGE(bufoff, gbase, voff) do { _Pragma("unroll") for (int _i = 0; _i < 2; ++_i) \
;         __builtin_amdgcn_global_load_lds((const unsigned*)((const char*)(gbase) + (voff)[_i]), (PG8_LAS unsigned*)(lds + (bufoff) + ldsw + _i * 8192), 16, 0, 0); } while (0)
; #define PG8_LDA(dst, b, h) do { _Pragma("unroll") for (int m = 0; m < 4; ++m) _Pragma("unroll") for (int k = 0; k < 2; ++k) dst[m][k] = *(const PG8_LAS bf16x8*)(lds + PG8_SA(b, h) + aoff + m * 2048 + k * 1024); } while (0)
; #define PG8_LDB(dst, b, h) do { _Pragma("unroll") for (int n = 0; n < 2; ++n) _Pragma("unroll") for (int k = 0; k < 2; ++k) dst[n][k] = *(const PG8_LAS bf16x8*)(lds + PG8_SB(b, h) + boff + n * 2048 + k * 1024); } while (0)
; #define PG8_MMA(ai, bj, At, Bt) do { __builtin_amdgcn_s_setprio(1); _Pragma("unroll") for (int m = 0; m < 4; ++m) _Pragma("unroll") for (int n = 0; n < 2; ++n) _Pragma("unroll") for (int k = 0; k < 2; ++k) \
;         acc[ai][bj][m][n] = __builtin_amdgcn_mfma_f32_16x16x32_bf16(Bt[n][k], At[m][k], acc[ai][bj][m][n], 0, 0, 0); __builtin_amdgcn_s_setprio(0); } while (0)
; #define PG8_WAIT_V(n) asm volatile("s_waitcnt vmcnt(" #n ")" ::: "memory")
; #define PG8_WAIT_L(n) asm volatile("s_waitcnt lgkmcnt(" #n ")" ::: "memory")
; #define PG8_BAR __builtin_amdgcn_s_barrier()
; #define PG8_SCHED __builtin_amdgcn_sched_barrier(0)
; template <class Epi, class Sched, bool ALIGN_EPI = false, bool SP2 = false>
; __device__ __forceinline__ void gemm_phase(PG8_LAS unsigned char* lds, const Gemm g, const Sched& S, const Epi& E) {
;     ...
;         for (int t = 0; t < nt; t += 2) {
;             const bool last = (t == nt - 2);
;             const char* a1 = cA + (size_t)(t + 1) * kstep;
;             const char* a2 = last ? nA : cA + (size_t)(t + 2) * kstep; const char* b2 = last ? nB : cB + (size_t)(t + 2) * kstep;
;     ...
;             PG8_LDB(B0, 1, 0); PG8_LDB(B1, 1, 1); PG8_SCHED; PG8_LDA(At, 1, 0); PG8_STAGE(PG8_SA(0, 1), a2 + hstep, voffA);
;             PG8_WAIT_V(8); PG8_WAIT_L(0); PG8_BAR; PG8_MMA(0, 0, At, B0); PG8_MMA(0, 1, At, B1); PG8_BAR; PG8_SCHED;
;             PG8_LDA(At, 1, 1); PG8_STAGE(PG8_SB(1, 0), b3, voffB); PG8_STAGE(PG8_SB(1, 1), b3 + hstep, voffB); PG8_STAGE(PG8_SA(1, 0), a3, voffA);
;             PG8_WAIT_V(8); PG8_WAIT_L(0); PG8_BAR; PG8_MMA(1, 0, At, B0); PG8_MMA(1, 1, At, B1); PG8_BAR; PG8_SCHED;
	s_add_i32 s47, 0, 0x18000
	v_add_u32_e32 v93, s47, v91
	ds_read_b128 v[18:21], v93
	ds_read_b128 v[22:25], v93 offset:1024
	ds_read_b128 v[94:97], v93 offset:2048
	ds_read_b128 v[98:101], v93 offset:3072
	s_add_u32 s24, s24, 0x40000
	s_addc_u32 s25, s25, 0
	s_mov_b32 m0, s34
	v_lshl_add_u64 v[140:141], s[24:25], 0, v[0:1]
	ds_read_b128 v[102:105], v92 offset:32768
	ds_read_b128 v[106:109], v92 offset:33792
	ds_read_b128 v[110:113], v92 offset:34816
	ds_read_b128 v[114:117], v92 offset:35840
	ds_read_b128 v[118:121], v92 offset:36864
	ds_read_b128 v[122:125], v92 offset:37888
	ds_read_b128 v[126:129], v92 offset:38912
	ds_read_b128 v[130:133], v92 offset:39936
	global_load_lds_dwordx4 v[140:141], off
	v_lshl_add_u64 v[140:141], s[24:25], 0, v[76:77]
	s_mov_b32 m0, s35
	s_nop 0
	global_load_lds_dwordx4 v[140:141], off
	s_waitcnt vmcnt(5)
	s_waitcnt lgkmcnt(0)
	s_barrier
	s_setprio 1
	s_waitcnt lgkmcnt(0)
	v_mfma_f32_16x16x32_bf16 v[70:73], v[18:21], v[102:105], v[70:73]
	v_mfma_f32_16x16x32_bf16 v[66:69], v[94:97], v[102:105], v[66:69]
	v_mfma_f32_16x16x32_bf16 v[62:65], v[18:21], v[110:113], v[62:65]
	v_mfma_f32_16x16x32_bf16 v[58:61], v[94:97], v[110:113], v[58:61]
	v_mfma_f32_16x16x32_bf16 v[54:57], v[18:21], v[118:121], v[54:57]
	v_mfma_f32_16x16x32_bf16 v[50:53], v[94:97], v[118:121], v[50:53]
	v_mfma_f32_16x16x32_bf16 v[46:49], v[18:21], v[126:129], v[46:49]
	v_mfma_f32_16x16x32_bf16 v[42:45], v[94:97], v[126:129], v[42:45]
	v_mfma_f32_16x16x32_bf16 v[70:73], v[22:25], v[106:109], v[70:73]
	v_mfma_f32_16x16x32_bf16 v[66:69], v[98:101], v[106:109], v[66:69]
	v_mfma_f32_16x16x32_bf16 v[62:65], v[22:25], v[114:117], v[62:65]
	v_mfma_f32_16x16x32_bf16 v[58:61], v[98:101], v[114:117], v[58:61]
	v_mfma_f32_16x16x32_bf16 v[54:57], v[22:25], v[122:125], v[54:57]
	v_mfma_f32_16x16x32_bf16 v[50:53], v[98:101], v[122:125], v[50:53]
	v_mfma_f32_16x16x32_bf16 v[46:49], v[22:25], v[130:133], v[46:49]
	v_mfma_f32_16x16x32_bf16 v[42:45], v[98:101], v[130:133], v[42:45]
	s_setprio 0
	s_setprio 1
	s_setprio 0
	s_barrier
	s_add_i32 s24, s47, s28
	v_lshl_add_u64 v[88:89], v[88:89], 0, s[84:85]
	s_mov_b32 m0, s24
	ds_read_b128 v[102:105], v92 offset:49152
	ds_read_b128 v[106:109], v92 offset:50176
	ds_read_b128 v[110:113], v92 offset:51200
	ds_read_b128 v[114:117], v92 offset:52224
	ds_read_b128 v[118:121], v92 offset:53248
	ds_read_b128 v[122:125], v92 offset:54272
	ds_read_b128 v[126:129], v92 offset:55296
	ds_read_b128 v[130:133], v92 offset:56320
	global_load_lds_dwordx4 v[88:89], off
	s_add_i32 m0, s24, 0x2000
	s_add_u32 s22, s22, 0x40080
	v_lshl_add_u64 v[88:89], v[134:135], 0, s[84:85]
	s_addc_u32 s23, s23, 0
	v_lshl_add_u64 v[88:89], s[22:23], 0, v[78:79]
	s_mov_b32 m0, s38
	s_nop 0
	v_lshl_add_u64 v[88:89], s[22:23], 0, v[74:75]
	s_mov_b32 m0, s39
	s_nop 0
	v_lshl_add_u64 v[88:89], v[136:137], 0, s[84:85]
	s_mov_b32 m0, s36
	s_nop 0
	global_load_lds_dwordx4 v[88:89], off
	v_lshl_add_u64 v[88:89], v[138:139], 0, s[84:85]
	s_mov_b32 m0, s37
	s_nop 0
	global_load_lds_dwordx4 v[88:89], off
	s_waitcnt vmcnt(5)
	s_waitcnt lgkmcnt(0)
	s_barrier
	s_setprio 1
	s_waitcnt lgkmcnt(0)
	v_mfma_f32_16x16x32_bf16 v[38:41], v[18:21], v[102:105], v[38:41]
	v_mfma_f32_16x16x32_bf16 v[34:37], v[94:97], v[102:105], v[34:37]
	v_mfma_f32_16x16x32_bf16 v[30:33], v[18:21], v[110:113], v[30:33]
	v_mfma_f32_16x16x32_bf16 v[26:29], v[94:97], v[110:113], v[26:29]
	v_mfma_f32_16x16x32_bf16 v[14:17], v[18:21], v[118:121], v[14:17]
	v_mfma_f32_16x16x32_bf16 v[10:13], v[94:97], v[118:121], v[10:13]
	v_mfma_f32_16x16x32_bf16 v[6:9], v[18:21], v[126:129], v[6:9]
	v_mfma_f32_16x16x32_bf16 v[2:5], v[94:97], v[126:129], v[2:5]
	v_mfma_f32_16x16x32_bf16 v[38:41], v[22:25], v[106:109], v[38:41]
	v_mfma_f32_16x16x32_bf16 v[34:37], v[98:101], v[106:109], v[34:37]
	v_mfma_f32_16x16x32_bf16 v[30:33], v[22:25], v[114:117], v[30:33]
	v_mfma_f32_16x16x32_bf16 v[26:29], v[98:101], v[114:117], v[26:29]
	v_mfma_f32_16x16x32_bf16 v[14:17], v[22:25], v[122:125], v[14:17]
	v_mfma_f32_16x16x32_bf16 v[10:13], v[98:101], v[122:125], v[10:13]
	v_mfma_f32_16x16x32_bf16 v[6:9], v[22:25], v[130:133], v[6:9]
	v_mfma_f32_16x16x32_bf16 v[2:5], v[98:101], v[130:133], v[2:5]
	s_setprio 0
	s_setprio 1
	s_setprio 0
	s_barrier
	s_add_i32 s46, s46, 2
	s_add_u32 s20, s20, 0x100
	s_addc_u32 s21, s21, 0
	s_add_u32 s44, s44, 0x100
	s_addc_u32 s45, s45, 0
	s_cmp_gt_u32 s46, 13
	s_cbranch_scc0 .LBB0_229
	s_and_b64 vcc, exec, s[10:11]
	s_cbranch_vccz .LBB0_232
	s_barrier
